# norm row loops: 64-lane sum of squares by DPP and permlane swaps instead of six LDS exchanges
# baseline (speedup 1.0000x reference)
; __device__ __forceinline__ float shx(float v, int mask, int lane) { return __builtin_bit_cast(float, __builtin_amdgcn_ds_bpermute((lane ^ mask) << 2, __builtin_bit_cast(int, v))); }
; DI float wave_sum(float v, int lane) {
; #pragma unroll
;     for (int o = 1; o < 64; o <<= 1) v += shx(v, o, lane);
;     return v;
; }
; DI void norm_phase(const float* xp, const float* xs, const float* gvec, const float* MODL  , int sc_off, bf16_t* H, int tid,
;                    const float* P, int nparts, const float* pgate, float* X) {
;     ...
;         for (int j = 0; j < 4; ++j) ss += v[j][0] * v[j][0] + v[j][1] * v[j][1] + v[j][2] * v[j][2] + v[j][3] * v[j][3];
;         const float r = rsqrtf(wave_sum(ss, lane) * (1.f / 1024.f) + 1e-6f);
.LBB0_16:
	s_or_b64 exec, exec, s[6:7]
	s_waitcnt vmcnt(0)
	v_pk_mul_f32 v[40:41], v[12:13], v[12:13]
	s_waitcnt vmcnt(2)
	v_pk_mul_f32 v[42:43], v[8:9], v[8:9]
	v_pk_mul_f32 v[36:37], v[14:15], v[14:15]
	v_pk_mul_f32 v[38:39], v[10:11], v[10:11]
	v_mov_b32_e32 v44, v40
	v_mov_b32_e32 v45, v42
	v_mov_b32_e32 v42, v41
	v_pk_add_f32 v[40:41], v[44:45], v[42:43]
	v_mov_b32_e32 v42, v36
	v_mov_b32_e32 v43, v38
	s_waitcnt vmcnt(0)
	v_pk_mul_f32 v[32:33], v[0:1], v[0:1]
	v_pk_mul_f32 v[34:35], v[4:5], v[4:5]
	v_pk_add_f32 v[40:41], v[42:43], v[40:41]
	v_mov_b32_e32 v38, v37
	v_pk_mul_f32 v[16:17], v[2:3], v[2:3]
	v_pk_mul_f32 v[18:19], v[6:7], v[6:7]
	v_pk_add_f32 v[36:37], v[38:39], v[40:41]
	v_mov_b32_e32 v38, v32
	v_mov_b32_e32 v39, v34
	v_mov_b32_e32 v34, v33
	v_pk_add_f32 v[32:33], v[38:39], v[34:35]
	v_mov_b32_e32 v34, v16
	v_mov_b32_e32 v35, v18
	v_pk_add_f32 v[32:33], v[34:35], v[32:33]
	v_mov_b32_e32 v18, v17
	v_pk_add_f32 v[16:17], v[18:19], v[32:33]
	global_load_dwordx4 v[32:35], v[28:29], off
	global_load_dwordx4 v[198:201], v[28:29], off offset:1024
	global_load_dwordx4 v[202:205], v[28:29], off offset:2048
	global_load_dwordx4 v[206:209], v[28:29], off offset:3072
	v_add_f32_e32 v18, v36, v37
	v_add_f32_e32 v17, v17, v18
	v_add_f32_e32 v16, v16, v17
	v_lshl_add_u64 v[20:21], v[20:21], 0, s[48:49]
	s_movk_i32 s6, 0x41ff
	s_nop 1
	v_add_f32_dpp v16, v16, v16 quad_perm:[1,0,3,2] row_mask:0xf bank_mask:0xf
	s_nop 1
	v_add_f32_dpp v16, v16, v16 quad_perm:[2,3,0,1] row_mask:0xf bank_mask:0xf
	s_nop 1
	v_add_f32_dpp v16, v16, v16 row_half_mirror row_mask:0xf bank_mask:0xf
	s_nop 1
	v_add_f32_dpp v16, v16, v16 row_mirror row_mask:0xf bank_mask:0xf
	v_mov_b32_e32 v17, v16
	s_nop 1
	v_permlane16_swap_b32_e32 v16, v17
	v_add_f32_e32 v16, v16, v17
	v_mov_b32_e32 v17, v16
	s_nop 1
	v_permlane32_swap_b32_e32 v16, v17
	v_add_f32_e32 v16, v16, v17
	v_mov_b32_e32 v17, 0x358637bd
	v_fmamk_f32 v16, v16, 0x3a800000, v17
	v_cmp_gt_f32_e32 vcc, s42, v16
	v_mul_f32_e32 v17, 0x4b800000, v16
	s_nop 0
	v_cndmask_b32_e32 v16, v16, v17, vcc
	v_rsq_f32_e32 v16, v16
	s_nop 0
	v_mul_f32_e32 v17, 0x45800000, v16
	v_cndmask_b32_e32 v16, v16, v17, vcc
	v_pk_mul_f32 v[12:13], v[12:13], v[16:17] op_sel_hi:[1,0]
	v_pk_mul_f32 v[14:15], v[14:15], v[16:17] op_sel_hi:[1,0]
	v_cmp_lt_i32_e32 vcc, s6, v20
	s_or_b64 s[4:5], vcc, s[4:5]
	s_waitcnt vmcnt(3)
	v_pk_mul_f32 v[14:15], v[34:35], v[14:15]
	v_pk_mul_f32 v[12:13], v[32:33], v[12:13]
	global_store_dwordx4 v[30:31], v[12:15], off
	v_pk_mul_f32 v[8:9], v[8:9], v[16:17] op_sel_hi:[1,0]
	v_pk_mul_f32 v[10:11], v[10:11], v[16:17] op_sel_hi:[1,0]
	s_waitcnt vmcnt(3)
	v_pk_mul_f32 v[8:9], v[198:199], v[8:9]
	v_pk_mul_f32 v[10:11], v[200:201], v[10:11]
	global_store_dwordx4 v[30:31], v[8:11], off offset:1024
	v_pk_mul_f32 v[4:5], v[4:5], v[16:17] op_sel_hi:[1,0]
	v_pk_mul_f32 v[6:7], v[6:7], v[16:17] op_sel_hi:[1,0]
	s_waitcnt vmcnt(3)
	v_pk_mul_f32 v[4:5], v[202:203], v[4:5]
	v_pk_mul_f32 v[6:7], v[204:205], v[6:7]
	global_store_dwordx4 v[30:31], v[4:7], off offset:2048
	v_pk_mul_f32 v[0:1], v[0:1], v[16:17] op_sel_hi:[1,0]
	v_pk_mul_f32 v[2:3], v[2:3], v[16:17] op_sel_hi:[1,0]
	s_waitcnt vmcnt(3)
	v_pk_mul_f32 v[0:1], v[206:207], v[0:1]
	v_pk_mul_f32 v[2:3], v[208:209], v[2:3]
	global_store_dwordx4 v[30:31], v[0:3], off offset:3072
	s_andn2_b64 exec, exec, s[4:5]
	s_cbranch_execz .LBB0_130

; __device__ __forceinline__ float shx(float v, int mask, int lane) { return __builtin_bit_cast(float, __builtin_amdgcn_ds_bpermute((lane ^ mask) << 2, __builtin_bit_cast(int, v))); }
; __device__ __forceinline__ void st_bf4(bf16_t* p, const f32x4 v) { u32x2 w; w.x = cvt_pk_bf16(v[0], v[1]); w.y = cvt_pk_bf16(v[2], v[3]); *(u32x2*)p = w; }
; DI float wave_sum(float v, int lane) {
; #pragma unroll
;     for (int o = 1; o < 64; o <<= 1) v += shx(v, o, lane);
;     return v;
; }
; DI void norm_phase(const float* xp, const float* xs, const float* gvec, const float* MODL  , int sc_off, bf16_t* H, int tid,
;                    const float* P, int nparts, const float* pgate, float* X) {
;     ...
;         for (int j = 0; j < 4; ++j) ss += v[j][0] * v[j][0] + v[j][1] * v[j][1] + v[j][2] * v[j][2] + v[j][3] * v[j][3];
;         const float r = rsqrtf(wave_sum(ss, lane) * (1.f / 1024.f) + 1e-6f);
;         if (H) {
; #pragma unroll
;             for (int j = 0; j < 4; ++j) { const int c = 4 * lane + 256 * j; const f32x4 g = *(const f32x4*)(gvec + c), sh = *(const f32x4*)(mr + c), sc = *(const f32x4*)(mr + sc_off + c);
;                 st_bf4(H + (size_t)row * 1024 + c, v[j] * r * g * (1.f + sc) + sh); }
.LBB0_227:
	s_or_b64 exec, exec, s[6:7]
	s_waitcnt vmcnt(0)
	v_pk_mul_f32 v[50:51], v[12:13], v[12:13]
	v_pk_mul_f32 v[52:53], v[8:9], v[8:9]
	v_pk_mul_f32 v[46:47], v[14:15], v[14:15]
	v_pk_mul_f32 v[48:49], v[10:11], v[10:11]
	v_mov_b32_e32 v60, v50
	v_mov_b32_e32 v61, v52
	v_mov_b32_e32 v52, v51
	v_pk_add_f32 v[50:51], v[60:61], v[52:53]
	v_mov_b32_e32 v52, v46
	v_mov_b32_e32 v53, v48
	v_pk_mul_f32 v[42:43], v[0:1], v[0:1]
	v_pk_mul_f32 v[44:45], v[4:5], v[4:5]
	v_pk_add_f32 v[50:51], v[52:53], v[50:51]
	v_mov_b32_e32 v48, v47
	v_lshl_add_u64 v[40:41], v[36:37], 2, s[4:5]
	v_pk_mul_f32 v[36:37], v[2:3], v[2:3]
	v_pk_mul_f32 v[38:39], v[6:7], v[6:7]
	v_pk_add_f32 v[46:47], v[48:49], v[50:51]
	v_mov_b32_e32 v48, v42
	v_mov_b32_e32 v49, v44
	v_mov_b32_e32 v44, v43
	v_pk_add_f32 v[42:43], v[48:49], v[44:45]
	v_mov_b32_e32 v44, v36
	v_mov_b32_e32 v45, v38
	v_pk_add_f32 v[42:43], v[44:45], v[42:43]
	v_mov_b32_e32 v38, v37
	s_mov_b64 s[6:7], 0x1000
	v_pk_add_f32 v[36:37], v[38:39], v[42:43]
	v_lshl_add_u64 v[38:39], v[40:41], 0, s[6:7]
	v_lshl_add_u64 v[40:41], v[40:41], 0, v[96:97]
	v_lshl_add_u64 v[50:51], v[38:39], 0, v[96:97]
	v_add_f32_e32 v29, v46, v47
	global_load_dwordx4 v[42:45], v[24:25], off
	global_load_dwordx4 v[46:49], v[40:41], off
	v_add_f32_e32 v29, v37, v29
	global_load_dwordx4 v[50:53], v[50:51], off
	global_load_dwordx4 v[198:201], v[24:25], off offset:1024
	global_load_dwordx4 v[210:213], v[40:41], off offset:1024
	v_mov_b32_e32 v234, v28
	v_mov_b32_e32 v235, v97
	v_lshl_add_u64 v[234:235], v[38:39], 0, v[234:235]
	global_load_dwordx4 v[222:225], v[234:235], off
	global_load_dwordx4 v[202:205], v[24:25], off offset:2048
	global_load_dwordx4 v[214:217], v[40:41], off offset:2048
	v_mov_b32_e32 v236, v30
	v_mov_b32_e32 v237, v97
	v_lshl_add_u64 v[236:237], v[38:39], 0, v[236:237]
	global_load_dwordx4 v[226:229], v[236:237], off
	global_load_dwordx4 v[206:209], v[24:25], off offset:3072
	global_load_dwordx4 v[218:221], v[40:41], off offset:3072
	v_mov_b32_e32 v238, v32
	v_mov_b32_e32 v239, v97
	v_lshl_add_u64 v[238:239], v[38:39], 0, v[238:239]
	global_load_dwordx4 v[230:233], v[238:239], off
	v_add_f32_e32 v29, v36, v29
	v_lshl_add_u64 v[34:35], v[34:35], 1, v[26:27]
	v_mov_b32_e32 v33, v97
	v_lshl_add_u64 v[16:17], v[16:17], 0, s[48:49]
	s_movk_i32 s6, 0x41ff
	s_nop 1
	v_add_f32_dpp v29, v29, v29 quad_perm:[1,0,3,2] row_mask:0xf bank_mask:0xf
	s_nop 1
	v_add_f32_dpp v29, v29, v29 quad_perm:[2,3,0,1] row_mask:0xf bank_mask:0xf
	s_nop 1
	v_add_f32_dpp v29, v29, v29 row_half_mirror row_mask:0xf bank_mask:0xf
	s_nop 1
	v_add_f32_dpp v29, v29, v29 row_mirror row_mask:0xf bank_mask:0xf
	v_mov_b32_e32 v31, v29
	s_nop 1
	v_permlane16_swap_b32_e32 v29, v31
	v_add_f32_e32 v29, v29, v31
	v_mov_b32_e32 v31, v29
	s_nop 1
	v_permlane32_swap_b32_e32 v29, v31
	v_add_f32_e32 v29, v29, v31
	v_mov_b32_e32 v31, 0x358637bd
	v_fmamk_f32 v29, v29, 0x3a800000, v31
	v_cmp_gt_f32_e32 vcc, s42, v29
	v_mul_f32_e32 v31, 0x4b800000, v29
	s_nop 0
	v_cndmask_b32_e32 v29, v29, v31, vcc
	v_rsq_f32_e32 v29, v29
	s_nop 0
	v_mul_f32_e32 v31, 0x45800000, v29
	v_cndmask_b32_e32 v36, v29, v31, vcc
	v_pk_mul_f32 v[14:15], v[14:15], v[36:37] op_sel_hi:[1,0]
	v_pk_mul_f32 v[12:13], v[12:13], v[36:37] op_sel_hi:[1,0]
	v_mov_b32_e32 v29, v97
	v_pk_mul_f32 v[10:11], v[10:11], v[36:37] op_sel_hi:[1,0]
	v_pk_mul_f32 v[8:9], v[8:9], v[36:37] op_sel_hi:[1,0]
	v_mov_b32_e32 v31, v97
	v_pk_mul_f32 v[6:7], v[6:7], v[36:37] op_sel_hi:[1,0]
	v_pk_mul_f32 v[4:5], v[4:5], v[36:37] op_sel_hi:[1,0]
	v_pk_mul_f32 v[2:3], v[2:3], v[36:37] op_sel_hi:[1,0]
	v_pk_mul_f32 v[0:1], v[0:1], v[36:37] op_sel_hi:[1,0]
	v_cmp_lt_i32_e32 vcc, s6, v16
	s_or_b64 s[8:9], vcc, s[8:9]
	s_waitcnt vmcnt(9)
	v_pk_mul_f32 v[12:13], v[42:43], v[12:13]
	v_pk_mul_f32 v[14:15], v[44:45], v[14:15]
	v_pk_add_f32 v[50:51], v[50:51], 1.0 op_sel_hi:[1,0]
	v_pk_add_f32 v[52:53], v[52:53], 1.0 op_sel_hi:[1,0]
	v_pk_fma_f32 v[12:13], v[50:51], v[12:13], v[46:47]
	v_pk_fma_f32 v[14:15], v[52:53], v[14:15], v[48:49]
	v_cvt_pk_bf16_f32 v12, v12, v13
	v_cvt_pk_bf16_f32 v13, v14, v15
	global_store_dwordx2 v[34:35], v[12:13], off
	s_waitcnt vmcnt(7)
	v_pk_mul_f32 v[8:9], v[198:199], v[8:9]
	v_pk_mul_f32 v[10:11], v[200:201], v[10:11]
	v_pk_add_f32 v[222:223], v[222:223], 1.0 op_sel_hi:[1,0]
	v_pk_add_f32 v[224:225], v[224:225], 1.0 op_sel_hi:[1,0]
	v_pk_fma_f32 v[8:9], v[222:223], v[8:9], v[210:211]
	v_pk_fma_f32 v[10:11], v[224:225], v[10:11], v[212:213]
	v_cvt_pk_bf16_f32 v8, v8, v9
	v_cvt_pk_bf16_f32 v9, v10, v11
	global_store_dwordx2 v[34:35], v[8:9], off offset:512
	s_waitcnt vmcnt(5)
	v_pk_mul_f32 v[4:5], v[202:203], v[4:5]
	v_pk_mul_f32 v[6:7], v[204:205], v[6:7]
	v_pk_add_f32 v[226:227], v[226:227], 1.0 op_sel_hi:[1,0]
	v_pk_add_f32 v[228:229], v[228:229], 1.0 op_sel_hi:[1,0]
	v_pk_fma_f32 v[4:5], v[226:227], v[4:5], v[214:215]
	v_pk_fma_f32 v[6:7], v[228:229], v[6:7], v[216:217]
	v_cvt_pk_bf16_f32 v4, v4, v5
	v_cvt_pk_bf16_f32 v5, v6, v7
	global_store_dwordx2 v[34:35], v[4:5], off offset:1024
	s_waitcnt vmcnt(3)
	v_pk_mul_f32 v[0:1], v[206:207], v[0:1]
	v_pk_mul_f32 v[2:3], v[208:209], v[2:3]
	v_pk_add_f32 v[230:231], v[230:231], 1.0 op_sel_hi:[1,0]
	v_pk_add_f32 v[232:233], v[232:233], 1.0 op_sel_hi:[1,0]
	v_pk_fma_f32 v[0:1], v[230:231], v[0:1], v[218:219]
	v_pk_fma_f32 v[2:3], v[232:233], v[2:3], v[220:221]
	v_cvt_pk_bf16_f32 v0, v0, v1
	v_cvt_pk_bf16_f32 v1, v2, v3
	global_store_dwordx2 v[34:35], v[0:1], off offset:1536
	s_andn2_b64 exec, exec, s[8:9]
	s_cbranch_execz .LBB0_230

; __device__ __forceinline__ float shx(float v, int mask, int lane) { return __builtin_bit_cast(float, __builtin_amdgcn_ds_bpermute((lane ^ mask) << 2, __builtin_bit_cast(int, v))); }
; __device__ __forceinline__ void st_bf4(bf16_t* p, const f32x4 v) { u32x2 w; w.x = cvt_pk_bf16(v[0], v[1]); w.y = cvt_pk_bf16(v[2], v[3]); *(u32x2*)p = w; }
; DI float wave_sum(float v, int lane) {
; #pragma unroll
;     for (int o = 1; o < 64; o <<= 1) v += shx(v, o, lane);
;     return v;
; }
; DI void norm_phase(const float* xp, const float* xs, const float* gvec, const float* MODL  , int sc_off, bf16_t* H, int tid,
;                    const float* P, int nparts, const float* pgate, float* X) {
;     ...
;         for (int j = 0; j < 4; ++j) ss += v[j][0] * v[j][0] + v[j][1] * v[j][1] + v[j][2] * v[j][2] + v[j][3] * v[j][3];
;         const float r = rsqrtf(wave_sum(ss, lane) * (1.f / 1024.f) + 1e-6f);
;         if (H) {
; #pragma unroll
;             for (int j = 0; j < 4; ++j) { const int c = 4 * lane + 256 * j; const f32x4 g = *(const f32x4*)(gvec + c), sh = *(const f32x4*)(mr + c), sc = *(const f32x4*)(mr + sc_off + c);
;                 st_bf4(H + (size_t)row * 1024 + c, v[j] * r * g * (1.f + sc) + sh); }
.LBB0_1952:
	s_or_b64 exec, exec, s[6:7]
	s_waitcnt vmcnt(0)
	v_pk_mul_f32 v[50:51], v[12:13], v[12:13]
	v_pk_mul_f32 v[52:53], v[8:9], v[8:9]
	v_pk_mul_f32 v[46:47], v[14:15], v[14:15]
	v_pk_mul_f32 v[48:49], v[10:11], v[10:11]
	v_mov_b32_e32 v54, v50
	v_mov_b32_e32 v55, v52
	v_mov_b32_e32 v52, v51
	v_pk_add_f32 v[50:51], v[54:55], v[52:53]
	v_mov_b32_e32 v52, v46
	v_mov_b32_e32 v53, v48
	v_pk_mul_f32 v[42:43], v[0:1], v[0:1]
	v_pk_mul_f32 v[44:45], v[4:5], v[4:5]
	v_pk_add_f32 v[50:51], v[52:53], v[50:51]
	v_mov_b32_e32 v48, v47
	v_pk_mul_f32 v[16:17], v[2:3], v[2:3]
	v_pk_mul_f32 v[18:19], v[6:7], v[6:7]
	v_pk_add_f32 v[46:47], v[48:49], v[50:51]
	v_mov_b32_e32 v48, v42
	v_mov_b32_e32 v49, v44
	v_mov_b32_e32 v44, v43
	v_pk_add_f32 v[42:43], v[48:49], v[44:45]
	v_mov_b32_e32 v44, v16
	v_mov_b32_e32 v45, v18
	v_pk_add_f32 v[42:43], v[44:45], v[42:43]
	v_mov_b32_e32 v18, v17
	v_lshl_add_u64 v[40:41], v[40:41], 2, s[2:3]
	v_pk_add_f32 v[16:17], v[18:19], v[42:43]
	v_add_f32_e32 v18, v46, v47
	s_mov_b64 s[6:7], 0x1000
	v_add_f32_e32 v17, v17, v18
	v_lshl_add_u64 v[18:19], v[40:41], 0, s[6:7]
	v_lshl_add_u64 v[40:41], v[40:41], 0, v[96:97]
	v_lshl_add_u64 v[50:51], v[18:19], 0, v[96:97]
	global_load_dwordx4 v[42:45], v[28:29], off
	global_load_dwordx4 v[46:49], v[40:41], off
	v_add_f32_e32 v16, v16, v17
	global_load_dwordx4 v[50:53], v[50:51], off
	global_load_dwordx4 v[198:201], v[28:29], off offset:1024
	global_load_dwordx4 v[210:213], v[40:41], off offset:1024
	v_mov_b32_e32 v234, v32
	v_mov_b32_e32 v235, v97
	v_lshl_add_u64 v[234:235], v[18:19], 0, v[234:235]
	global_load_dwordx4 v[222:225], v[234:235], off
	global_load_dwordx4 v[202:205], v[28:29], off offset:2048
	global_load_dwordx4 v[214:217], v[40:41], off offset:2048
	v_mov_b32_e32 v236, v34
	v_mov_b32_e32 v237, v97
	v_lshl_add_u64 v[236:237], v[18:19], 0, v[236:237]
	global_load_dwordx4 v[226:229], v[236:237], off
	global_load_dwordx4 v[206:209], v[28:29], off offset:3072
	global_load_dwordx4 v[218:221], v[40:41], off offset:3072
	v_mov_b32_e32 v238, v36
	v_mov_b32_e32 v239, v97
	v_lshl_add_u64 v[238:239], v[18:19], 0, v[238:239]
	global_load_dwordx4 v[230:233], v[238:239], off
	v_lshl_add_u64 v[38:39], v[38:39], 1, v[30:31]
	v_mov_b32_e32 v33, v97
	v_mov_b32_e32 v35, v97
	v_mov_b32_e32 v37, v97
	s_nop 1
	v_add_f32_dpp v16, v16, v16 quad_perm:[1,0,3,2] row_mask:0xf bank_mask:0xf
	v_lshl_add_u64 v[20:21], v[20:21], 0, s[48:49]
	s_movk_i32 s6, 0x41ff
	s_nop 1
	v_add_f32_dpp v16, v16, v16 quad_perm:[2,3,0,1] row_mask:0xf bank_mask:0xf
	s_nop 1
	v_add_f32_dpp v16, v16, v16 row_half_mirror row_mask:0xf bank_mask:0xf
	s_nop 1
	v_add_f32_dpp v16, v16, v16 row_mirror row_mask:0xf bank_mask:0xf
	v_mov_b32_e32 v17, v16
	s_nop 1
	v_permlane16_swap_b32_e32 v16, v17
	v_add_f32_e32 v16, v16, v17
	v_mov_b32_e32 v17, v16
	s_nop 1
	v_permlane32_swap_b32_e32 v16, v17
	v_add_f32_e32 v16, v16, v17
	v_mov_b32_e32 v17, 0x358637bd
	v_fmamk_f32 v16, v16, 0x3a800000, v17
	v_cmp_gt_f32_e32 vcc, s42, v16
	v_mul_f32_e32 v17, 0x4b800000, v16
	s_nop 0
	v_cndmask_b32_e32 v16, v16, v17, vcc
	v_rsq_f32_e32 v16, v16
	s_nop 0
	v_mul_f32_e32 v17, 0x45800000, v16
	v_cndmask_b32_e32 v16, v16, v17, vcc
	v_pk_mul_f32 v[14:15], v[14:15], v[16:17] op_sel_hi:[1,0]
	v_pk_mul_f32 v[12:13], v[12:13], v[16:17] op_sel_hi:[1,0]
	v_pk_mul_f32 v[10:11], v[10:11], v[16:17] op_sel_hi:[1,0]
	v_pk_mul_f32 v[8:9], v[8:9], v[16:17] op_sel_hi:[1,0]
	v_pk_mul_f32 v[6:7], v[6:7], v[16:17] op_sel_hi:[1,0]
	v_pk_mul_f32 v[4:5], v[4:5], v[16:17] op_sel_hi:[1,0]
	v_pk_mul_f32 v[2:3], v[2:3], v[16:17] op_sel_hi:[1,0]
	v_pk_mul_f32 v[0:1], v[0:1], v[16:17] op_sel_hi:[1,0]
	v_cmp_lt_i32_e32 vcc, s6, v20
	s_or_b64 s[4:5], vcc, s[4:5]
	s_waitcnt vmcnt(9)
	v_pk_mul_f32 v[12:13], v[42:43], v[12:13]
	v_pk_mul_f32 v[14:15], v[44:45], v[14:15]
	v_pk_add_f32 v[50:51], v[50:51], 1.0 op_sel_hi:[1,0]
	v_pk_add_f32 v[52:53], v[52:53], 1.0 op_sel_hi:[1,0]
	v_pk_fma_f32 v[12:13], v[50:51], v[12:13], v[46:47]
	v_pk_fma_f32 v[14:15], v[52:53], v[14:15], v[48:49]
	v_cvt_pk_bf16_f32 v12, v12, v13
	v_cvt_pk_bf16_f32 v13, v14, v15
	global_store_dwordx2 v[38:39], v[12:13], off
	s_waitcnt vmcnt(7)
	v_pk_mul_f32 v[8:9], v[198:199], v[8:9]
	v_pk_mul_f32 v[10:11], v[200:201], v[10:11]
	v_pk_add_f32 v[222:223], v[222:223], 1.0 op_sel_hi:[1,0]
	v_pk_add_f32 v[224:225], v[224:225], 1.0 op_sel_hi:[1,0]
	v_pk_fma_f32 v[8:9], v[222:223], v[8:9], v[210:211]
	v_pk_fma_f32 v[10:11], v[224:225], v[10:11], v[212:213]
	v_cvt_pk_bf16_f32 v8, v8, v9
	v_cvt_pk_bf16_f32 v9, v10, v11
	global_store_dwordx2 v[38:39], v[8:9], off offset:512
	s_waitcnt vmcnt(5)
	v_pk_mul_f32 v[4:5], v[202:203], v[4:5]
	v_pk_mul_f32 v[6:7], v[204:205], v[6:7]
	v_pk_add_f32 v[226:227], v[226:227], 1.0 op_sel_hi:[1,0]
	v_pk_add_f32 v[228:229], v[228:229], 1.0 op_sel_hi:[1,0]
	v_pk_fma_f32 v[4:5], v[226:227], v[4:5], v[214:215]
	v_pk_fma_f32 v[6:7], v[228:229], v[6:7], v[216:217]
	v_cvt_pk_bf16_f32 v4, v4, v5
	v_cvt_pk_bf16_f32 v5, v6, v7
	global_store_dwordx2 v[38:39], v[4:5], off offset:1024
	s_waitcnt vmcnt(3)
	v_pk_mul_f32 v[0:1], v[206:207], v[0:1]
	v_pk_mul_f32 v[2:3], v[208:209], v[2:3]
	v_pk_add_f32 v[230:231], v[230:231], 1.0 op_sel_hi:[1,0]
	v_pk_add_f32 v[232:233], v[232:233], 1.0 op_sel_hi:[1,0]
	v_pk_fma_f32 v[0:1], v[230:231], v[0:1], v[218:219]
	v_pk_fma_f32 v[2:3], v[232:233], v[2:3], v[220:221]
	v_cvt_pk_bf16_f32 v0, v0, v1
	v_cvt_pk_bf16_f32 v1, v2, v3
	global_store_dwordx2 v[38:39], v[0:1], off offset:1536
	s_andn2_b64 exec, exec, s[4:5]
	s_cbranch_execz .LBB0_1955
